# MLA loop: the per-tile workgroup barrier replaced by a per-half LDS arrive/spin counter so the two 4-wave halves (different heads) run decoupled
# speedup vs baseline: 1.0443x; 1.0036x over previous
; DI int tid_op() { int t = threadIdx.x & 255; asm volatile("" : "+v"(t)); return t; }
;     constexpr int KS = DQK + 8, NKS = DQK / 16, KCH = DQK / 8, NKL = 64 * KCH / 256;
;     const int tid = tid_op(), lane = tid & 63, w = tid >> 6, r = lane & 31, h = lane >> 5;
;     const int qidx = q0 + 32 * w + r;
;     bf16x8 qf[NKS];
; #pragma unroll
;     for (int s = 0; s < NKS; ++s) qf[s] = *(const bf16x8*)(Q + (size_t)(32 * w + r) * DQK + 16 * s + 8 * h);
;     float qn = 0.f;
;     if (MODE == 0 && DESC) {
; #pragma unroll
;         for (int s = 0; s < NKS; ++s)
; #pragma unroll
;             for (int j = 0; j < 8; ++j) { const float a = __uint_as_float(((unsigned)(unsigned short)qf[s][j]) << 16); qn += a * a; }
;         qn += xhalf_other(qn, h);
;         qn = sqrtf(qn) * kmax;
;     }
;     f32x16 o0, o1;
; #pragma unroll
;     for (int i = 0; i < 16; ++i) { o0[i] = 0.f; o1[i] = 0.f; }
;     float m = -INFINITY, lsum = 0.f, R = 1.f;
;     u32x4 rk[NKL], rv[2]; f32x4 rc = {0.f, 0.f, 0.f, 0.f};
;     const unsigned okk = (unsigned)(((tid / KCH) * DQK + (tid % KCH) * 8) * 2);
;     const unsigned ovv = (unsigned)(((tid >> 3) * ldv + (tid & 7) * 8) * 2), svv = (unsigned)(ldv * 64);
;     auto ld_tile = [&](int kt) {
;         const unsigned char* Kt = (const unsigned char*)(K + (size_t)(64 * kt) * DQK);
;         const unsigned char* Vt = (const unsigned char*)(VT + 64 * kt);
; #pragma unroll
;         for (int j = 0; j < NKL; ++j) rk[j] = *(const u32x4*)(Kt + (okk + j * 4096));
; #pragma unroll
;         for (int j = 0; j < 2; ++j) rv[j] = *(const u32x4*)(Vt + (ovv + j * svv));
;         if (cdec && tid < 16) rc = *(const f32x4*)(cdec + 64 * kt + 4 * tid);
;     };
;     auto st_tile = [&](int buf) {
;         bf16_t* sK = (bf16_t*)(smem + buf * ATT_BUF); bf16_t* sV = (bf16_t*)(smem + buf * ATT_BUF + 13312); float* sC = (float*)(smem + buf * ATT_BUF + 22528);
; #pragma unroll
;         for (int j = 0; j < NKL; ++j) { const int c = tid + 256 * j, row = c / KCH, kc = (c % KCH) * 8; *(u32x4*)(sK + row * KS + kc) = rk[j]; }
; #pragma unroll
;         for (int j = 0; j < 2; ++j) { const int c = tid + 256 * j, row = c >> 3, kc = (c & 7) * 8; *(u32x4*)(sV + row * LS + kc) = rv[j]; }
;         if (cdec && tid < 16) *(f32x4*)(sC + 4 * tid) = rc;
;     };
;     ld_tile(DESC ? ntiles - 1 : 0);
;     __syncthreads();
;     st_tile(0);
.LBB0_771:
	s_and_b64 vcc, exec, s[4:5]
	s_cbranch_vccz .LBB0_786
	s_lshl_b64 s[4:5], s[10:11], 13
	s_or_b32 s4, s4, s94
	s_mulk_i32 s5, 0xc0
	s_mul_hi_u32 s6, s4, 0xc0
	s_add_i32 s5, s6, s5
	s_mulk_i32 s4, 0xc0
	v_readlane_b32 s0, v254, 58
	s_add_u32 s6, s0, s4
	v_readlane_b32 s0, v254, 59
	v_mov_b32_e32 v8, v215
	s_addc_u32 s7, s0, s5
	s_mul_i32 s4, s10, 0x180000
	v_ashrrev_i32_e32 v9, 1, v8
	v_readlane_b32 s0, v254, 60
	v_bfe_u32 v121, v8, 5, 1
	v_bfi_b32 v110, s41, v9, v8
	v_mov_b64_e32 v[2:3], s[6:7]
	s_mul_hi_u32 s5, s10, 0x180000
	s_add_u32 s4, s0, s4
	v_readlane_b32 s0, v254, 61
	v_mad_i64_i32 v[2:3], s[6:7], v110, s85, v[2:3]
	v_lshlrev_b32_e32 v0, 4, v121
	s_addc_u32 s5, s0, s5
	v_lshl_add_u64 v[2:3], v[2:3], 0, v[0:1]
	v_lshlrev_b32_e32 v0, 4, v8
	v_lshl_add_u64 v[4:5], s[4:5], 0, v[0:1]
	v_add_u32_e32 v112, 0x1000, v0
	v_mov_b32_e32 v113, v1
	v_lshl_add_u64 v[6:7], s[4:5], 0, v[112:113]
	global_load_dwordx4 v[66:69], v[4:5], off
	global_load_dwordx4 v[70:73], v[6:7], off
	v_add_u32_e32 v114, 0x2000, v0
	v_mov_b32_e32 v115, v1
	s_lshl_b64 s[6:7], s[10:11], 20
	v_lshl_add_u64 v[4:5], s[4:5], 0, v[114:115]
	v_readlane_b32 s0, v254, 62
	global_load_dwordx4 v[74:77], v[4:5], off
	s_add_u32 s6, s0, s6
	v_readlane_b32 s0, v254, 63
	s_addc_u32 s7, s0, s7
	v_lshlrev_b32_e32 v4, 11, v8
	v_and_b32_e32 v5, 0x70, v0
	s_movk_i32 s0, 0xc000
	v_and_or_b32 v116, v4, s0, v5
	v_mov_b32_e32 v117, v1
	v_lshl_add_u64 v[4:5], s[6:7], 0, v[116:117]
	global_load_dwordx4 v[78:81], v[4:5], off
	v_add_u32_e32 v118, 0x80000, v116
	v_mov_b32_e32 v119, v1
	v_lshl_add_u64 v[4:5], s[6:7], 0, v[118:119]
	global_load_dwordx4 v[82:85], v[4:5], off
	global_load_dwordx4 v[86:89], v[2:3], off
	global_load_dwordx4 v[90:93], v[2:3], off offset:32
	global_load_dwordx4 v[94:97], v[2:3], off offset:64
	global_load_dwordx4 v[98:101], v[2:3], off offset:96
	global_load_dwordx4 v[102:105], v[2:3], off offset:128
	global_load_dwordx4 v[106:109], v[2:3], off offset:160
	s_add_u32 s14, s4, 0x3000
	s_addc_u32 s15, s5, 0
	global_load_dwordx4 v[176:179], v0, s[14:15]
	global_load_dwordx4 v[180:183], v112, s[14:15]
	global_load_dwordx4 v[184:187], v114, s[14:15]
	s_mov_b32 s0, 0x2aaaaaab
	v_mul_hi_i32 v5, v8, s0
	v_add_u32_e32 v6, 0x100, v8
	v_add_u32_e32 v7, 0x200, v8
	v_lshrrev_b32_e32 v11, 31, v5
	v_ashrrev_i32_e32 v5, 1, v5
	v_mul_hi_i32 v12, v6, s0
	v_and_b32_e32 v9, 0xffffffe0, v9
	v_mul_hi_i32 v13, v7, s0
	v_add_u32_e32 v2, v5, v11
	v_lshrrev_b32_e32 v3, 31, v12
	v_ashrrev_i32_e32 v5, 1, v12
	s_movk_i32 s0, 0x68
	v_add_u32_e32 v125, s94, v9
	v_lshrrev_b32_e32 v9, 31, v13
	v_ashrrev_i32_e32 v11, 1, v13
	v_mul_lo_u32 v12, v2, 12
	v_mul_lo_u32 v2, v2, s0
	v_add_u32_e32 v3, v5, v3
	v_add_u32_e32 v5, v11, v9
	v_sub_u32_e32 v9, v8, v12
	v_lshlrev_b32_e32 v127, 1, v2
	v_mul_lo_u32 v2, v3, 12
	v_mul_lo_u32 v3, v3, s0
	v_lshlrev_b32_e32 v11, 3, v9
	v_lshlrev_b32_e32 v9, 4, v9
	v_sub_u32_e32 v2, v6, v2
	v_lshlrev_b32_e32 v128, 1, v3
	v_add3_u32 v3, s33, v127, v9
	v_lshlrev_b32_e32 v9, 3, v2
	v_lshlrev_b32_e32 v2, 4, v2
	v_add3_u32 v2, s33, v128, v2
	s_waitcnt lgkmcnt(0)
	s_barrier
;     ...
;     f32x16 o0, o1;
; #pragma unroll
;     for (int i = 0; i < 16; ++i) { o0[i] = 0.f; o1[i] = 0.f; }
;     float m = -INFINITY, lsum = 0.f, R = 1.f;
;     u32x4 rk[NKL], rv[2]; f32x4 rc = {0.f, 0.f, 0.f, 0.f};
;     const unsigned okk = (unsigned)(((tid / KCH) * DQK + (tid % KCH) * 8) * 2);
;     const unsigned ovv = (unsigned)(((tid >> 3) * ldv + (tid & 7) * 8) * 2), svv = (unsigned)(ldv * 64);
;     auto ld_tile = [&](int kt) {
;         const unsigned char* Kt = (const unsigned char*)(K + (size_t)(64 * kt) * DQK);
;         const unsigned char* Vt = (const unsigned char*)(VT + 64 * kt);
; #pragma unroll
;         for (int j = 0; j < NKL; ++j) rk[j] = *(const u32x4*)(Kt + (okk + j * 4096));
; #pragma unroll
;         for (int j = 0; j < 2; ++j) rv[j] = *(const u32x4*)(Vt + (ovv + j * svv));
;         if (cdec && tid < 16) rc = *(const f32x4*)(cdec + 64 * kt + 4 * tid);
;     };
;     auto st_tile = [&](int buf) {
;         bf16_t* sK = (bf16_t*)(smem + buf * ATT_BUF); bf16_t* sV = (bf16_t*)(smem + buf * ATT_BUF + 13312); float* sC = (float*)(smem + buf * ATT_BUF + 22528);
; #pragma unroll
;         for (int j = 0; j < NKL; ++j) { const int c = tid + 256 * j, row = c / KCH, kc = (c % KCH) * 8; *(u32x4*)(sK + row * KS + kc) = rk[j]; }
; #pragma unroll
;         for (int j = 0; j < 2; ++j) { const int c = tid + 256 * j, row = c >> 3, kc = (c & 7) * 8; *(u32x4*)(sV + row * LS + kc) = rv[j]; }
;         if (cdec && tid < 16) *(f32x4*)(sC + 4 * tid) = rc;
;     };
;     ld_tile(DESC ? ntiles - 1 : 0);
;     __syncthreads();
;     st_tile(0);
	v_and_b32_e32 v4, 31, v8
	v_lshlrev_b32_e32 v10, 3, v121
	s_waitcnt vmcnt(0)
	ds_write_b128 v3, v[66:69]
	ds_write_b128 v2, v[70:73]
	v_mul_lo_u32 v2, v5, 12
	v_sub_u32_e32 v2, v7, v2
	v_mul_lo_u32 v5, v5, s0
	v_lshlrev_b32_e32 v3, 3, v2
	v_lshlrev_b32_e32 v129, 1, v5
	v_lshlrev_b32_e32 v2, 4, v2
	v_add3_u32 v2, s33, v129, v2
	ds_write_b128 v2, v[74:77]
	v_lshrrev_b32_e32 v2, 3, v8
	v_lshlrev_b32_e32 v5, 3, v8
	s_movk_i32 s0, 0x48
	v_and_b32_e32 v5, 56, v5
	v_mul_lo_u32 v2, v2, s0
	v_lshlrev_b32_e32 v130, 1, v2
	v_lshlrev_b32_e32 v131, 1, v5
	v_and_b32_e32 v217, 1, v215
	v_lshlrev_b32_e32 v217, 3, v217
	v_sub_u32_e32 v217, v131, v217
	v_add_u32_e32 v217, 0x3400, v217
	v_add3_u32 v2, s33, v130, v217
	ds_write2_b64 v2, v[78:79], v[80:81] offset1:2
	v_lshrrev_b32_e32 v2, 3, v6
	v_mul_lo_u32 v2, v2, s0
	v_lshlrev_b32_e32 v132, 1, v2
	v_add3_u32 v2, s33, v132, v217
	v_mov_b32_e32 v18, v1
	v_mov_b32_e32 v19, v1
	v_or_b32_e32 v126, v125, v4
	ds_write2_b64 v2, v[82:83], v[84:85] offset1:2
	v_mul_u32_u24_e32 v134, 0xd0, v4
	v_mul_u32_u24_e32 v136, 0x90, v4
	v_mov_b32_e32 v20, v1
	v_mov_b32_e32 v21, v1
	v_mov_b32_e32 v22, v1
	v_mov_b32_e32 v23, v1
	v_mov_b32_e32 v24, v1
	v_mov_b32_e32 v25, v1
	v_mov_b32_e32 v26, v1
	v_mov_b32_e32 v27, v1
	v_mov_b32_e32 v28, v1
	v_mov_b32_e32 v29, v1
	v_mov_b32_e32 v30, v1
	v_mov_b32_e32 v31, v1
	v_mov_b32_e32 v32, v1
	v_mov_b32_e32 v33, v1
	v_lshlrev_b32_e32 v137, 1, v10
	v_lshlrev_b32_e32 v138, 1, v11
	v_lshlrev_b32_e32 v139, 1, v9
	v_lshlrev_b32_e32 v140, 1, v3
	v_mov_b64_e32 v[2:3], v[18:19]
	s_mov_b32 s95, s49
	v_ashrrev_i32_e32 v111, 31, v110
	v_or_b32_e32 v133, 31, v125
	v_lshlrev_b32_e32 v123, 2, v121
	s_mov_b32 s16, 0
	v_mov_b32_e32 v135, 0
	v_mov_b32_e32 v122, 0xff800000
	s_mov_b32 s12, 0
	v_mov_b64_e32 v[4:5], v[20:21]
	v_mov_b64_e32 v[6:7], v[22:23]
	v_mov_b64_e32 v[8:9], v[24:25]
	v_mov_b64_e32 v[10:11], v[26:27]
	v_mov_b64_e32 v[12:13], v[28:29]
	v_mov_b64_e32 v[14:15], v[30:31]
	v_mov_b64_e32 v[16:17], v[32:33]
	v_mov_b32_e32 v156, 0
	v_mov_b32_e32 v157, 0
	v_mov_b32_e32 v158, 0
	v_mov_b32_e32 v159, 0
	v_mov_b32_e32 v160, 0
	v_mov_b32_e32 v161, 0
	v_mov_b32_e32 v162, 0
	v_mov_b32_e32 v163, 0
	v_mov_b32_e32 v164, 0
	v_mov_b32_e32 v165, 0
	v_mov_b32_e32 v166, 0
	v_mov_b32_e32 v167, 0
	v_mov_b32_e32 v168, 0
	v_mov_b32_e32 v169, 0
	v_mov_b32_e32 v170, 0
	v_mov_b32_e32 v171, 0
	s_mov_b64 s[20:21], -1
	v_add3_u32 v127, s33, v127, v138
	v_add3_u32 v128, s33, v128, v139
	v_add3_u32 v129, s33, v129, v140
	v_add3_u32 v130, s33, v130, v217
	v_add3_u32 v132, s33, v132, v217
	v_add_u32_e32 v138, 0x5900, v130
	v_add_u32_e32 v139, 0x5900, v132
	v_add3_u32 v216, s33, v134, v137
	v_lshlrev_b32_e32 v231, 2, v123
	v_add3_u32 v231, s33, v136, v231
	s_lshr_b32 s31, s72, 1
	s_add_i32 s31, s31, 0x122c0
	v_mov_b32_e32 v155, s31
	v_mov_b32_e32 v172, 1
	v_mov_b32_e32 v173, 0
	ds_write_b32 v155, v173
	s_mov_b32 s30, 0
	ds_write_b128 v127, v[176:179] offset:22784
	ds_write_b128 v128, v[180:183] offset:22784
	ds_write_b128 v129, v[184:187] offset:22784
	s_waitcnt lgkmcnt(0)
	s_barrier
	ds_read_b128 v[208:211], v216 offset:0
	ds_read_b128 v[232:235], v216 offset:6656
	ds_read_b128 v[236:239], v216 offset:32
	ds_read_b128 v[240:243], v216 offset:6688
	ds_read_b128 v[244:247], v216 offset:64
	ds_read_b128 v[248:251], v216 offset:6720
	s_waitcnt lgkmcnt(4)
	v_mfma_f32_32x32x16_bf16 v[50:65], v[208:211], v[86:89], 0
	v_mfma_f32_32x32x16_bf16 v[34:49], v[232:235], v[86:89], 0
	ds_read_b128 v[208:211], v216 offset:96
	ds_read_b128 v[232:235], v216 offset:6752
	s_waitcnt lgkmcnt(4)
	v_mfma_f32_32x32x16_bf16 v[50:65], v[236:239], v[90:93], v[50:65]
	v_mfma_f32_32x32x16_bf16 v[34:49], v[240:243], v[90:93], v[34:49]
	ds_read_b128 v[236:239], v216 offset:128
	ds_read_b128 v[240:243], v216 offset:6784
	s_waitcnt lgkmcnt(4)
	v_mfma_f32_32x32x16_bf16 v[50:65], v[244:247], v[94:97], v[50:65]
	v_mfma_f32_32x32x16_bf16 v[34:49], v[248:251], v[94:97], v[34:49]
	ds_read_b128 v[244:247], v216 offset:160
	ds_read_b128 v[248:251], v216 offset:6816
	s_waitcnt lgkmcnt(4)
	v_mfma_f32_32x32x16_bf16 v[50:65], v[208:211], v[98:101], v[50:65]
	v_mfma_f32_32x32x16_bf16 v[34:49], v[232:235], v[98:101], v[34:49]
	s_waitcnt lgkmcnt(2)
	v_mfma_f32_32x32x16_bf16 v[50:65], v[236:239], v[102:105], v[50:65]
	v_mfma_f32_32x32x16_bf16 v[34:49], v[240:243], v[102:105], v[34:49]
	s_waitcnt lgkmcnt(0)
	v_mfma_f32_32x32x16_bf16 v[50:65], v[244:247], v[106:109], v[50:65]
	v_mfma_f32_32x32x16_bf16 v[34:49], v[248:251], v[106:109], v[34:49]
	s_nop 7
	s_nop 3

;     ...
;     for (int it = 0; it < ntiles; ++it) {
;         const int kt = DESC ? ntiles - 1 - it : it, buf = it & 1;
;         if (it + 1 < ntiles) ld_tile(DESC ? kt - 1 : kt + 1);
;         __syncthreads();
;     ...
;                 if (MODE == 0 && (64 * kt + 63 > q0 + 32 * w)) {
; #pragma unroll
;                     for (int mt = 0; mt < 2; ++mt)
; #pragma unroll
;                         for (int qd = 0; qd < 4; ++qd)
; #pragma unroll
;                             for (int e = 0; e < 4; ++e)
;                                 if (64 * kt + 32 * mt + 8 * qd + 4 * h + e > qidx) s4[mt][qd][e] = -INFINITY;
;                 }
.Lm3_even_nok:
	s_waitcnt lgkmcnt(0)
	s_mov_b64 s[26:27], exec
	s_mov_b64 exec, 1
	ds_add_u32 v155, v172
	s_mov_b64 exec, s[26:27]
	s_add_u32 s30, s30, 4
.Lm3_spin_0:
	ds_read_b32 v173, v155
	s_waitcnt lgkmcnt(0)
	v_readfirstlane_b32 s31, v173
	s_cmp_lt_u32 s31, s30
	s_cbranch_scc1 .Lm3_spin_0
	s_cmp_lt_u32 s17, s66
	s_cselect_b64 s[24:25], -1, 0
	ds_read_b128 v[208:211], v216 offset:22784
	ds_read_b128 v[232:235], v216 offset:29440
	ds_read_b128 v[236:239], v216 offset:22816
	ds_read_b128 v[240:243], v216 offset:29472
	ds_read_b128 v[244:247], v216 offset:22848
	ds_read_b128 v[248:251], v216 offset:29504
	s_add_i32 s14, s16, 63
	v_cmp_gt_i32_e32 vcc, s14, v125
	s_and_saveexec_b64 s[14:15], vcc
	s_cbranch_execz .Lm3_nomask_e
	v_sub_u32_e32 v213, v126, v123
	v_subrev_u32_e32 v213, s16, v213
	v_cmp_le_i32_e32 vcc, 0, v213
	s_nop 1
	v_cndmask_b32_e32 v50, v228, v50, vcc
	v_cmp_le_i32_e32 vcc, 1, v213
	s_nop 1
	v_cndmask_b32_e32 v51, v228, v51, vcc
	v_cmp_le_i32_e32 vcc, 2, v213
	s_nop 1
	v_cndmask_b32_e32 v52, v228, v52, vcc
	v_cmp_le_i32_e32 vcc, 3, v213
	s_nop 1
	v_cndmask_b32_e32 v53, v228, v53, vcc
	v_cmp_le_i32_e32 vcc, 8, v213
	s_nop 1
	v_cndmask_b32_e32 v54, v228, v54, vcc
	v_cmp_le_i32_e32 vcc, 9, v213
	s_nop 1
	v_cndmask_b32_e32 v55, v228, v55, vcc
	v_cmp_le_i32_e32 vcc, 10, v213
	s_nop 1
	v_cndmask_b32_e32 v56, v228, v56, vcc
	v_cmp_le_i32_e32 vcc, 11, v213
	s_nop 1
	v_cndmask_b32_e32 v57, v228, v57, vcc
	v_cmp_le_i32_e32 vcc, 16, v213
	s_nop 1
	v_cndmask_b32_e32 v58, v228, v58, vcc
	v_cmp_le_i32_e32 vcc, 17, v213
	s_nop 1
	v_cndmask_b32_e32 v59, v228, v59, vcc
	v_cmp_le_i32_e32 vcc, 18, v213
	s_nop 1
	v_cndmask_b32_e32 v60, v228, v60, vcc
	v_cmp_le_i32_e32 vcc, 19, v213
	s_nop 1
	v_cndmask_b32_e32 v61, v228, v61, vcc
	v_cmp_le_i32_e32 vcc, 24, v213
	s_nop 1
	v_cndmask_b32_e32 v62, v228, v62, vcc
	v_cmp_le_i32_e32 vcc, 25, v213
	s_nop 1
	v_cndmask_b32_e32 v63, v228, v63, vcc
	v_cmp_le_i32_e32 vcc, 26, v213
	s_nop 1
	v_cndmask_b32_e32 v64, v228, v64, vcc
	v_cmp_le_i32_e32 vcc, 27, v213
	s_nop 1
	v_cndmask_b32_e32 v65, v228, v65, vcc
	v_cmp_le_i32_e32 vcc, 32, v213
	s_nop 1
	v_cndmask_b32_e32 v34, v228, v34, vcc
	v_cmp_le_i32_e32 vcc, 33, v213
	s_nop 1
	v_cndmask_b32_e32 v35, v228, v35, vcc
	v_cmp_le_i32_e32 vcc, 34, v213
	s_nop 1
	v_cndmask_b32_e32 v36, v228, v36, vcc
	v_cmp_le_i32_e32 vcc, 35, v213
	s_nop 1
	v_cndmask_b32_e32 v37, v228, v37, vcc
	v_cmp_le_i32_e32 vcc, 40, v213
	s_nop 1
	v_cndmask_b32_e32 v38, v228, v38, vcc
	v_cmp_le_i32_e32 vcc, 41, v213
	s_nop 1
	v_cndmask_b32_e32 v39, v228, v39, vcc
	v_cmp_le_i32_e32 vcc, 42, v213
	s_nop 1
	v_cndmask_b32_e32 v40, v228, v40, vcc
	v_cmp_le_i32_e32 vcc, 43, v213
	s_nop 1
	v_cndmask_b32_e32 v41, v228, v41, vcc
	v_cmp_le_i32_e32 vcc, 48, v213
	s_nop 1
	v_cndmask_b32_e32 v42, v228, v42, vcc
	v_cmp_le_i32_e32 vcc, 49, v213
	s_nop 1
	v_cndmask_b32_e32 v43, v228, v43, vcc
	v_cmp_le_i32_e32 vcc, 50, v213
	s_nop 1
	v_cndmask_b32_e32 v44, v228, v44, vcc
	v_cmp_le_i32_e32 vcc, 51, v213
	s_nop 1
	v_cndmask_b32_e32 v45, v228, v45, vcc
	v_cmp_le_i32_e32 vcc, 56, v213
	s_nop 1
	v_cndmask_b32_e32 v46, v228, v46, vcc
	v_cmp_le_i32_e32 vcc, 57, v213
	s_nop 1
	v_cndmask_b32_e32 v47, v228, v47, vcc
	v_cmp_le_i32_e32 vcc, 58, v213
	s_nop 1
	v_cndmask_b32_e32 v48, v228, v48, vcc
	v_cmp_le_i32_e32 vcc, 59, v213
	s_nop 1
	v_cndmask_b32_e32 v49, v228, v49, vcc

;     ...
;     for (int it = 0; it < ntiles; ++it) {
;         const int kt = DESC ? ntiles - 1 - it : it, buf = it & 1;
;         if (it + 1 < ntiles) ld_tile(DESC ? kt - 1 : kt + 1);
;         __syncthreads();
;     ...
;                 float mx = fmaxf(s4[0][0].x, s4[1][0].x);
; #pragma unroll
;                 for (int qd = 0; qd < 4; ++qd) {
;                     mx = fmaxf(fmaxf(mx, s4[0][qd].y), s4[1][qd].y);
;                     mx = fmaxf(fmaxf(mx, s4[0][qd].z), s4[1][qd].z);
;                     mx = fmaxf(fmaxf(mx, s4[0][qd].w), s4[1][qd].w);
;                     if (qd < 3) mx = fmaxf(fmaxf(mx, s4[0][qd + 1].x), s4[1][qd + 1].x);
;                 }
;                 mx = xhalf_max(mx);
;                 const float mn = fmaxf(m, mx), alpha = fexp2(m - mn);
;                 m = mn;
;                 f32x4 ps4 = {0.f, 0.f, 0.f, 0.f};
;                 const float nmn = -mn;
;                 const f32x4 nm4 = {nmn, nmn, nmn, nmn};
;                 if (__builtin_amdgcn_ballot_w64(alpha != 1.f) != 0) { o0 *= alpha; o1 *= alpha; }
; #pragma unroll
;                 for (int s2 = 0; s2 < 4; ++s2) {
;                     const int mt = s2 >> 1, s = s2 & 1;
;                     f32x4 da = s4[mt][2 * s] + nm4, db = s4[mt][2 * s + 1] + nm4;
;                     da.x = fexp2(da.x); da.y = fexp2(da.y); da.z = fexp2(da.z); da.w = fexp2(da.w);
;                     db.x = fexp2(db.x); db.y = fexp2(db.y); db.z = fexp2(db.z); db.w = fexp2(db.w);
;                     ps4 += da; ps4 += db;
;                     u32x4 pp;
;                     pp.x = pk2(da.x, da.y); pp.y = pk2(da.z, da.w); pp.z = pk2(db.x, db.y); pp.w = pk2(db.z, db.w);
;                     const bf16x8 pfr = __builtin_bit_cast(bf16x8, pp);
;                     const s16x4 a0 = *(const s16x4*)(sV + r * LS + 16 * s2 + 4 * h), a1 = *(const s16x4*)(sV + r * LS + 16 * s2 + 8 + 4 * h);
;                     const s16x4 b0 = *(const s16x4*)(sV + (32 + r) * LS + 16 * s2 + 4 * h), b1 = *(const s16x4*)(sV + (32 + r) * LS + 16 * s2 + 8 + 4 * h);
;                     const bf16x8 v0 = __builtin_shufflevector(a0, a1, 0, 1, 2, 3, 4, 5, 6, 7), v1 = __builtin_shufflevector(b0, b1, 0, 1, 2, 3, 4, 5, 6, 7);
;                     o0 = MFMA32(v0, pfr, o0);
;                     o1 = MFMA32(v1, pfr, o1);
;                 }
;                 lsum = lsum * alpha + ((ps4.x + ps4.y) + (ps4.z + ps4.w));
.Lm3_back_e:
	s_waitcnt lgkmcnt(4)
	v_mfma_f32_32x32x16_bf16 v[176:191], v[208:211], v[86:89], v[156:171]
	v_exp_f32_e32 v50, v50
	v_exp_f32_e32 v51, v51
	v_exp_f32_e32 v52, v52
	v_mfma_f32_32x32x16_bf16 v[192:207], v[232:235], v[86:89], v[156:171]
	ds_read_b128 v[208:211], v216 offset:22880
	ds_read_b128 v[232:235], v216 offset:29536
	v_exp_f32_e32 v53, v53
	v_exp_f32_e32 v54, v54
	v_exp_f32_e32 v55, v55
	s_waitcnt lgkmcnt(4)
	v_mfma_f32_32x32x16_bf16 v[176:191], v[236:239], v[90:93], v[176:191]
	v_exp_f32_e32 v56, v56
	v_exp_f32_e32 v57, v57
	v_cvt_pk_bf16_f32 v142, v50, v51
	v_mfma_f32_32x32x16_bf16 v[192:207], v[240:243], v[90:93], v[192:207]
	ds_read_b128 v[236:239], v231 offset:13312
	ds_read_b128 v[240:243], v231 offset:17920
	v_cvt_pk_bf16_f32 v143, v52, v53
	v_cvt_pk_bf16_f32 v144, v54, v55
	v_cvt_pk_bf16_f32 v145, v56, v57
	v_exp_f32_e32 v58, v58
	s_waitcnt lgkmcnt(4)
	v_mfma_f32_32x32x16_bf16 v[176:191], v[244:247], v[94:97], v[176:191]
	v_exp_f32_e32 v59, v59
	v_exp_f32_e32 v60, v60
	v_exp_f32_e32 v61, v61
	v_mfma_f32_32x32x16_bf16 v[192:207], v[248:251], v[94:97], v[192:207]
	ds_read_b128 v[244:247], v216 offset:22912
	ds_read_b128 v[248:251], v216 offset:29568
	v_exp_f32_e32 v62, v62
	v_exp_f32_e32 v63, v63
	v_exp_f32_e32 v64, v64
	s_waitcnt lgkmcnt(4)
	v_mfma_f32_32x32x16_bf16 v[176:191], v[208:211], v[98:101], v[176:191]
	v_exp_f32_e32 v65, v65
	v_cvt_pk_bf16_f32 v146, v58, v59
	v_cvt_pk_bf16_f32 v147, v60, v61
	v_cvt_pk_bf16_f32 v148, v62, v63
	v_mfma_f32_32x32x16_bf16 v[192:207], v[232:235], v[98:101], v[192:207]
	ds_read_b128 v[208:211], v231 offset:13344
	ds_read_b128 v[232:235], v231 offset:17952
	v_cvt_pk_bf16_f32 v149, v64, v65
	v_exp_f32_e32 v34, v34
	v_exp_f32_e32 v35, v35
	s_waitcnt lgkmcnt(4)
	v_mfma_f32_32x32x16_bf16 v[18:33], v[236:239], v[142:145], v[18:33]
	v_exp_f32_e32 v36, v36
	v_exp_f32_e32 v37, v37
	v_exp_f32_e32 v38, v38
	v_mfma_f32_32x32x16_bf16 v[2:17], v[240:243], v[142:145], v[2:17]
	ds_read_b128 v[236:239], v216 offset:22944
	ds_read_b128 v[240:243], v216 offset:29600
	v_exp_f32_e32 v39, v39
	v_exp_f32_e32 v40, v40
	v_exp_f32_e32 v41, v41
	s_waitcnt lgkmcnt(4)
	v_mfma_f32_32x32x16_bf16 v[176:191], v[244:247], v[102:105], v[176:191]
	v_cvt_pk_bf16_f32 v150, v34, v35
	v_cvt_pk_bf16_f32 v151, v36, v37
	v_cvt_pk_bf16_f32 v152, v38, v39
	v_cvt_pk_bf16_f32 v153, v40, v41
	v_exp_f32_e32 v42, v42
	v_mfma_f32_32x32x16_bf16 v[192:207], v[248:251], v[102:105], v[192:207]
	s_waitcnt vmcnt(0)
	ds_write2_b64 v138, v[78:79], v[80:81] offset1:2
	ds_read_b128 v[244:247], v231 offset:13376
	ds_read_b128 v[248:251], v231 offset:17984
	v_exp_f32_e32 v43, v43
	v_exp_f32_e32 v44, v44
	v_exp_f32_e32 v45, v45
	s_waitcnt lgkmcnt(5)
	v_mfma_f32_32x32x16_bf16 v[18:33], v[208:211], v[146:149], v[18:33]
	ds_write2_b64 v139, v[82:83], v[84:85] offset1:2
	v_exp_f32_e32 v46, v46
	v_exp_f32_e32 v47, v47
	v_mfma_f32_32x32x16_bf16 v[2:17], v[232:235], v[146:149], v[2:17]
	ds_read_b128 v[208:211], v231 offset:13408
	ds_read_b128 v[232:235], v231 offset:18016
	v_exp_f32_e32 v48, v48
	v_exp_f32_e32 v49, v49
	v_cvt_pk_bf16_f32 v142, v42, v43
	v_cvt_pk_bf16_f32 v143, v44, v45
	s_waitcnt lgkmcnt(6)
	v_mfma_f32_32x32x16_bf16 v[176:191], v[236:239], v[106:109], v[176:191]
	s_mov_b64 exec, s[24:25]
	ds_write_b128 v127, v[66:69]
	ds_write_b128 v128, v[70:73]
	ds_write_b128 v129, v[74:77]
	s_mov_b64 exec, -1
	v_cvt_pk_bf16_f32 v144, v46, v47
	v_cvt_pk_bf16_f32 v145, v48, v49
	v_add_f32_e32 v141, v50, v51
	v_add_f32_e32 v154, v52, v53
	v_add_f32_e32 v212, v54, v55
	v_add_f32_e32 v213, v56, v57
	v_mfma_f32_32x32x16_bf16 v[192:207], v[240:243], v[106:109], v[192:207]
	v_add_f32_e32 v141, v141, v154
	v_add_f32_e32 v212, v212, v213
	v_add_f32_e32 v230, v141, v212
	v_add_f32_e32 v141, v58, v59
	v_add_f32_e32 v154, v60, v61
	v_add_f32_e32 v212, v62, v63
	s_waitcnt lgkmcnt(6)
	v_mfma_f32_32x32x16_bf16 v[18:33], v[244:247], v[150:153], v[18:33]
	v_add_f32_e32 v213, v64, v65
	v_add_f32_e32 v141, v141, v154
	v_add_f32_e32 v212, v212, v213
	v_add_f32_e32 v141, v141, v212
	v_add_f32_e32 v230, v230, v141
	v_mfma_f32_32x32x16_bf16 v[2:17], v[248:251], v[150:153], v[2:17]
	v_add_f32_e32 v141, v34, v35
	v_add_f32_e32 v154, v36, v37
	v_add_f32_e32 v212, v38, v39
	v_add_f32_e32 v213, v40, v41
	v_add_f32_e32 v141, v141, v154
	v_add_f32_e32 v212, v212, v213
	s_waitcnt lgkmcnt(3)
	v_mfma_f32_32x32x16_bf16 v[18:33], v[208:211], v[142:145], v[18:33]
	v_add_f32_e32 v141, v141, v212
	v_add_f32_e32 v230, v230, v141
	v_add_f32_e32 v141, v42, v43
	v_add_f32_e32 v154, v44, v45
	v_add_f32_e32 v212, v46, v47
	v_mfma_f32_32x32x16_bf16 v[2:17], v[232:235], v[142:145], v[2:17]
	v_add_f32_e32 v213, v48, v49
	v_add_f32_e32 v141, v141, v154
	v_add_f32_e32 v212, v212, v213
	v_add_f32_e32 v141, v141, v212
	v_add_f32_e32 v230, v230, v141
	v_add_f32_e32 v135, v135, v230
	s_add_i32 s12, s12, 1
	s_add_i32 s16, s16, 64
	s_add_i32 s17, s12, 1
	s_cmp_ge_u32 s17, s66
	s_cbranch_scc1 .Lm3_final
	s_add_i32 s48, s16, 64
	s_lshl_b64 s[14:15], s[48:49], 1
	s_add_u32 s14, s6, s14
	s_addc_u32 s15, s7, s15
	global_load_dwordx4 v[78:81], v116, s[14:15]
	global_load_dwordx4 v[82:85], v118, s[14:15]
	s_add_i32 s48, s16, 0x80
	s_mul_i32 s14, s48, 0xc0
	s_mul_hi_u32 s13, s48, 0xc0
	s_add_u32 s14, s4, s14
	s_addc_u32 s15, s5, s13
	global_load_dwordx4 v[66:69], v0, s[14:15]
	global_load_dwordx4 v[70:73], v112, s[14:15]
	global_load_dwordx4 v[74:77], v114, s[14:15]
	s_waitcnt lgkmcnt(0)
	s_mov_b64 s[26:27], exec
	s_mov_b64 exec, 1
	ds_add_u32 v155, v172
	s_mov_b64 exec, s[26:27]
	s_add_u32 s30, s30, 4
.Lm3_spin_1:
	ds_read_b32 v173, v155
	s_waitcnt lgkmcnt(0)
	v_readfirstlane_b32 s31, v173
	s_cmp_lt_u32 s31, s30
	s_cbranch_scc1 .Lm3_spin_1
	ds_read_b128 v[208:211], v216 offset:0
	ds_read_b128 v[232:235], v216 offset:6656
	ds_read_b128 v[236:239], v216 offset:32
	ds_read_b128 v[240:243], v216 offset:6688
	ds_read_b128 v[244:247], v216 offset:64
	ds_read_b128 v[248:251], v216 offset:6720
	v_max3_f32 v120, v176, v177, v178
	v_max3_f32 v141, v179, v180, v181
	v_max3_f32 v154, v182, v183, v184
	v_max3_f32 v212, v185, v186, v187
	v_max3_f32 v120, v120, v188, v189
	v_max3_f32 v141, v141, v190, v191
	v_max3_f32 v154, v154, v192, v193
	v_max3_f32 v212, v212, v194, v195
	v_max3_f32 v120, v120, v196, v197
	v_max3_f32 v141, v141, v198, v199
	v_max3_f32 v154, v154, v200, v201
	v_max3_f32 v212, v212, v202, v203
	v_max3_f32 v120, v120, v204, v205
	v_max3_f32 v141, v141, v206, v207
	v_max3_f32 v120, v120, v141, v154
	v_max_f32_e32 v120, v120, v212
	v_mov_b32_e32 v141, v120
	s_nop 1
	v_permlane32_swap_b32_e32 v120, v141
	v_max_f32_e32 v120, v120, v141
	v_cmp_lt_f32_e32 vcc, 0x41000000, v120
	s_or_b64 vcc, vcc, s[20:21]
	s_cbranch_vccnz .Lm3_rare_o

;     ...
;                 if (MODE == 0 && (64 * kt + 63 > q0 + 32 * w)) {
; #pragma unroll
;                     for (int mt = 0; mt < 2; ++mt)
; #pragma unroll
;                         for (int qd = 0; qd < 4; ++qd)
; #pragma unroll
;                             for (int e = 0; e < 4; ++e)
;                                 if (64 * kt + 32 * mt + 8 * qd + 4 * h + e > qidx) s4[mt][qd][e] = -INFINITY;
;                 }
.Lm3_final:
	v_cmp_le_i32_e32 vcc, s16, v133
	s_waitcnt lgkmcnt(0)
	s_mov_b64 s[26:27], exec
	s_mov_b64 exec, 1
	ds_add_u32 v155, v172
	s_mov_b64 exec, s[26:27]
	s_add_u32 s30, s30, 4
.Lm3_spin_2:
	ds_read_b32 v173, v155
	s_waitcnt lgkmcnt(0)
	v_readfirstlane_b32 s31, v173
	s_cmp_lt_u32 s31, s30
	s_cbranch_scc1 .Lm3_spin_2
	s_and_saveexec_b64 s[12:13], vcc
	s_cbranch_execz .Lm3_done
	ds_read_b128 v[208:211], v231 offset:36096
	ds_read_b128 v[232:235], v231 offset:40704
	ds_read_b128 v[236:239], v231 offset:36128
	ds_read_b128 v[240:243], v231 offset:40736
	ds_read_b128 v[244:247], v231 offset:36160
	ds_read_b128 v[248:251], v231 offset:40768
	s_add_i32 s14, s16, 63
	v_cmp_gt_i32_e32 vcc, s14, v125
	s_and_saveexec_b64 s[14:15], vcc
	s_cbranch_execz .Lm3_nomask_f
	v_sub_u32_e32 v213, v126, v123
	v_subrev_u32_e32 v213, s16, v213
	v_cmp_le_i32_e32 vcc, 0, v213
	s_nop 1
	v_cndmask_b32_e32 v176, v228, v176, vcc
	v_cmp_le_i32_e32 vcc, 1, v213
	s_nop 1
	v_cndmask_b32_e32 v177, v228, v177, vcc
	v_cmp_le_i32_e32 vcc, 2, v213
	s_nop 1
	v_cndmask_b32_e32 v178, v228, v178, vcc
	v_cmp_le_i32_e32 vcc, 3, v213
	s_nop 1
	v_cndmask_b32_e32 v179, v228, v179, vcc
	v_cmp_le_i32_e32 vcc, 8, v213
	s_nop 1
	v_cndmask_b32_e32 v180, v228, v180, vcc
	v_cmp_le_i32_e32 vcc, 9, v213
	s_nop 1
	v_cndmask_b32_e32 v181, v228, v181, vcc
	v_cmp_le_i32_e32 vcc, 10, v213
	s_nop 1
	v_cndmask_b32_e32 v182, v228, v182, vcc
	v_cmp_le_i32_e32 vcc, 11, v213
	s_nop 1
	v_cndmask_b32_e32 v183, v228, v183, vcc
	v_cmp_le_i32_e32 vcc, 16, v213
	s_nop 1
	v_cndmask_b32_e32 v184, v228, v184, vcc
	v_cmp_le_i32_e32 vcc, 17, v213
	s_nop 1
	v_cndmask_b32_e32 v185, v228, v185, vcc
	v_cmp_le_i32_e32 vcc, 18, v213
	s_nop 1
	v_cndmask_b32_e32 v186, v228, v186, vcc
	v_cmp_le_i32_e32 vcc, 19, v213
	s_nop 1
	v_cndmask_b32_e32 v187, v228, v187, vcc
	v_cmp_le_i32_e32 vcc, 24, v213
	s_nop 1
	v_cndmask_b32_e32 v188, v228, v188, vcc
	v_cmp_le_i32_e32 vcc, 25, v213
	s_nop 1
	v_cndmask_b32_e32 v189, v228, v189, vcc
	v_cmp_le_i32_e32 vcc, 26, v213
	s_nop 1
	v_cndmask_b32_e32 v190, v228, v190, vcc
	v_cmp_le_i32_e32 vcc, 27, v213
	s_nop 1
	v_cndmask_b32_e32 v191, v228, v191, vcc
	v_cmp_le_i32_e32 vcc, 32, v213
	s_nop 1
	v_cndmask_b32_e32 v192, v228, v192, vcc
	v_cmp_le_i32_e32 vcc, 33, v213
	s_nop 1
	v_cndmask_b32_e32 v193, v228, v193, vcc
	v_cmp_le_i32_e32 vcc, 34, v213
	s_nop 1
	v_cndmask_b32_e32 v194, v228, v194, vcc
	v_cmp_le_i32_e32 vcc, 35, v213
	s_nop 1
	v_cndmask_b32_e32 v195, v228, v195, vcc
	v_cmp_le_i32_e32 vcc, 40, v213
	s_nop 1
	v_cndmask_b32_e32 v196, v228, v196, vcc
	v_cmp_le_i32_e32 vcc, 41, v213
	s_nop 1
	v_cndmask_b32_e32 v197, v228, v197, vcc
	v_cmp_le_i32_e32 vcc, 42, v213
	s_nop 1
	v_cndmask_b32_e32 v198, v228, v198, vcc
	v_cmp_le_i32_e32 vcc, 43, v213
	s_nop 1
	v_cndmask_b32_e32 v199, v228, v199, vcc
	v_cmp_le_i32_e32 vcc, 48, v213
	s_nop 1
	v_cndmask_b32_e32 v200, v228, v200, vcc
	v_cmp_le_i32_e32 vcc, 49, v213
	s_nop 1
	v_cndmask_b32_e32 v201, v228, v201, vcc
	v_cmp_le_i32_e32 vcc, 50, v213
	s_nop 1
	v_cndmask_b32_e32 v202, v228, v202, vcc
	v_cmp_le_i32_e32 vcc, 51, v213
	s_nop 1
	v_cndmask_b32_e32 v203, v228, v203, vcc
	v_cmp_le_i32_e32 vcc, 56, v213
	s_nop 1
	v_cndmask_b32_e32 v204, v228, v204, vcc
	v_cmp_le_i32_e32 vcc, 57, v213
	s_nop 1
	v_cndmask_b32_e32 v205, v228, v205, vcc
	v_cmp_le_i32_e32 vcc, 58, v213
	s_nop 1
	v_cndmask_b32_e32 v206, v228, v206, vcc
	v_cmp_le_i32_e32 vcc, 59, v213
	s_nop 1
	v_cndmask_b32_e32 v207, v228, v207, vcc
